# one round of the w_in_c conversion moved out of P0 into the MRG-end barrier wait (workgroups without sample rows) and onto the 4-unit prompt workgroups at the ATT-end barrier
# speedup vs baseline: 1.0889x; 1.0064x over previous
.LBB0_10:
	s_cmp_lg_u32 s98, 0
	s_cbranch_scc1 .Lp0_noskip
	s_cmp_lg_u32 s97, 0x100
	s_cbranch_scc1 .Lp0_noskip
	s_add_i32 s0, s44, 0xffffe000
	s_cmp_lt_u32 s0, 0x1000
	s_cbranch_scc1 .LBB0_9

.Ltr_b2:
	s_cmp_eq_u32 s98, 3
	s_cbranch_scc1 .Lb3_ret
	s_cmp_eq_u32 s98, 9
	s_cbranch_scc1 .Lb3_ret
	s_cmp_eq_u32 s98, 2
	s_cbranch_scc1 .Lb4_ret
	s_branch .Ltr_b3

.Lb3_ret:
	s_cmp_eq_u32 s98, 9
	s_cbranch_scc1 .Lb3_fin
	v_readlane_b32 s7, v255, 2
	v_readlane_b32 s6, v255, 7
	s_nop 0
	s_lshr_b32 s7, s7, 6
	s_and_b32 s48, s6, 31
	s_cmp_lt_u32 s48, 16
	s_cbranch_scc1 .Lb3_fin
	s_add_i32 s48, s48, -16
	s_lshr_b32 s92, s6, 5
	s_lshl_b32 s92, s92, 2
	s_add_i32 s92, s92, s48
	s_mul_i32 s92, s92, 7
	s_add_i32 s92, s92, s7
	s_add_i32 s92, s92, 0x2e8f
	s_mov_b32 s98, 9
	s_mov_b32 s99, 0x2fff
	s_movk_i32 s48, 0xe0
	v_readlane_b32 s0, v255, 3
	v_readlane_b32 s1, v255, 4
	v_readlane_b32 s2, v255, 0
	v_readlane_b32 s3, v255, 1
	s_mov_b64 exec, -1
	v_and_b32_e32 v162, 63, v0
	s_lshl_b32 s30, s7, 14
	s_nop 4
	s_branch .Ltr_f2

.LBB0_1001:
	s_or_b64 exec, exec, s[2:3]
	s_waitcnt vmcnt(0)
	s_barrier
	s_cmp_eq_u32 s97, 0x100
	s_cbranch_scc0 .Lb4_skip
	v_readlane_b32 s7, v255, 2
	v_readlane_b32 s6, v255, 7
	s_nop 0
	s_lshr_b32 s7, s7, 6
	s_cmp_eq_u32 s7, 0
	s_cbranch_scc1 .Lb4_skip
	s_cmp_lt_u32 s6, 16
	s_cbranch_scc1 .Lb4_skip
	v_writelane_b32 v186, s14, 0
	v_writelane_b32 v186, s15, 1
	v_writelane_b32 v186, s30, 2
	v_writelane_b32 v186, s34, 3
	v_writelane_b32 v186, s92, 4
	v_writelane_b32 v186, exec_lo, 5
	v_writelane_b32 v186, exec_hi, 6
	s_mov_b64 exec, -1
	v_mov_b32_e32 v167, v1
	v_mov_b32_e32 v168, v5
	v_mov_b32_e32 v169, v21
	v_mov_b32_e32 v170, v24
	v_mov_b32_e32 v171, v25
	v_mov_b32_e32 v172, v26
	v_mov_b32_e32 v173, v27
	v_mov_b32_e32 v174, v30
	v_mov_b32_e32 v175, v31
	v_mov_b32_e32 v176, v34
	v_mov_b32_e32 v177, v35
	v_mov_b32_e32 v178, v47
	v_mov_b32_e32 v179, v48
	v_mov_b32_e32 v180, v49
	v_mov_b32_e32 v181, v73
	v_mov_b32_e32 v182, v86
	v_mov_b32_e32 v183, v87
	v_mov_b32_e32 v184, v104
	v_mov_b32_e32 v185, v105
	s_add_i32 s92, s6, -16
	s_mul_i32 s92, s92, 7
	s_add_i32 s92, s92, s7
	s_add_i32 s92, s92, 0x27ff
	s_mov_b64 s[100:101], s[4:5]
	s_mov_b32 s98, 2
	s_mov_b32 s99, 0x2fff
	s_movk_i32 s48, 0x1000
	v_readlane_b32 s0, v255, 3
	v_readlane_b32 s1, v255, 4
	v_readlane_b32 s2, v255, 0
	v_readlane_b32 s3, v255, 1
	v_mov_b32_e32 v163, v0
	v_and_b32_e32 v162, 63, v0
	s_lshl_b32 s30, s7, 14
	s_nop 4
	s_branch .Ltr_f2
.Lb4_ret:
	s_mov_b32 s98, 0
	s_mov_b64 s[4:5], s[100:101]
	s_mov_b64 exec, -1
	v_mov_b32_e32 v1, v167
	v_mov_b32_e32 v5, v168
	v_mov_b32_e32 v21, v169
	v_mov_b32_e32 v24, v170
	v_mov_b32_e32 v25, v171
	v_mov_b32_e32 v26, v172
	v_mov_b32_e32 v27, v173
	v_mov_b32_e32 v30, v174
	v_mov_b32_e32 v31, v175
	v_mov_b32_e32 v34, v176
	v_mov_b32_e32 v35, v177
	v_mov_b32_e32 v47, v178
	v_mov_b32_e32 v48, v179
	v_mov_b32_e32 v49, v180
	v_mov_b32_e32 v73, v181
	v_mov_b32_e32 v86, v182
	v_mov_b32_e32 v87, v183
	v_mov_b32_e32 v104, v184
	v_mov_b32_e32 v105, v185
	v_readlane_b32 s14, v186, 0
	v_readlane_b32 s15, v186, 1
	v_readlane_b32 s30, v186, 2
	v_readlane_b32 s34, v186, 3
	v_readlane_b32 s92, v186, 4
	v_readlane_b32 s6, v186, 5
	v_readlane_b32 s7, v186, 6
	s_nop 1
	s_mov_b64 exec, s[6:7]
